# mainloop SP2 load phase: counted waits moved after the trailing address VALU
# speedup vs baseline: 1.0279x; 1.0032x over previous
; #define PG8_LDA(dst, b, h) do { _Pragma("unroll") for (int m = 0; m < 4; ++m) _Pragma("unroll") for (int k = 0; k < 2; ++k) dst[m][k] = *(const LAS bf16x8*)(lds + PG8_SA(b, h) + aoff + m * 2048 + k * 1024); } while (0)
; #define PG8_LDB(dst, b, h) do { _Pragma("unroll") for (int n = 0; n < 2; ++n) _Pragma("unroll") for (int k = 0; k < 2; ++k) dst[n][k] = *(const LAS bf16x8*)(lds + PG8_SB(b, h) + boff + n * 2048 + k * 1024); } while (0)
; #define PG8_MMA(ai, bj, At, Bt) do { __builtin_amdgcn_s_setprio(1); _Pragma("unroll") for (int m = 0; m < 4; ++m) _Pragma("unroll") for (int n = 0; n < 2; ++n) _Pragma("unroll") for (int k = 0; k < 2; ++k) \
;         acc[ai][bj][m][n] = __builtin_amdgcn_mfma_f32_16x16x32_bf16(Bt[n][k], At[m][k], acc[ai][bj][m][n], 0, 0, 0); __builtin_amdgcn_s_setprio(0); } while (0)
; #define PG8_WAIT_V(n) asm volatile("s_waitcnt vmcnt(" #n ")" ::: "memory")
; #define PG8_WAIT_L(n) asm volatile("s_waitcnt lgkmcnt(" #n ")" ::: "memory")
; #define PG8_BAR __builtin_amdgcn_s_barrier()
; #define PG8_SCHED __builtin_amdgcn_sched_barrier(0)
; #define PG8_STA(bufoff, gbase, ld) PG8_STAGE(bufoff, gbase, RA0 * (unsigned)(ld) + CC0, RA1 * (unsigned)(ld) + CC1)
; __device__ __forceinline__ void gemm_phase(LAS unsigned char* lds, const Sched& S, const Epi& E) {
;     ...
;         for (int t = 0; t < nt_main; t += 2) {
;             const bool last = (t == nt - 2);
;             const char* a1 = cA + (size_t)(t + 1) * kstep;
;             const char* a2 = last ? nA : cA + (size_t)(t + 2) * kstep; const char* b2 = last ? nB : cB + (size_t)(t + 2) * kstep;
;             const char* a3 = a2 + kstep; const char* b3 = b2 + kstep;
;             const int xlda = last ? nlda : lda, xldb = last ? nldb : ldb;
;             const size_t xhA = (size_t)HALF * xlda * 2, xhB = (size_t)HALF * xldb * 2;
;             PG8_LDB(B0, 0, 0); PG8_LDB(B1, 0, 1); PG8_SCHED; PG8_LDA(At, 0, 0); PG8_STA(PG8_SA(1, 1), a1 + hA, lda);
;             PG8_WAIT_V(8); PG8_WAIT_L(0); PG8_BAR; PG8_MMA(0, 0, At, B0); PG8_MMA(0, 1, At, B1); PG8_BAR; PG8_SCHED;
;             PG8_LDA(At, 0, 1); PG8_STB(PG8_SB(0, 0), b2, xldb); PG8_STB(PG8_SB(0, 1), b2 + xhB, xldb); PG8_STA(PG8_SA(0, 0), a2, xlda);
;             PG8_WAIT_V(8); PG8_WAIT_L(0); PG8_BAR; PG8_MMA(1, 0, At, B0); PG8_MMA(1, 1, At, B1); PG8_BAR; PG8_SCHED;
.LBB0_263:
	s_add_i32 s24, s8, 2
	s_add_u32 s26, vcc_lo, 0x80
	s_addc_u32 s9, vcc_hi, 0
	s_add_i32 s37, 0, 0x10000
	s_cmp_eq_u32 s21, s8
	s_cselect_b32 s9, s7, s9
	s_cselect_b32 s8, s6, s26
	s_cselect_b32 s92, s11, s61
	s_cselect_b32 s30, s22, s20
	v_add_u32_e32 v0, s37, v241
	s_cselect_b32 s29, s13, s72
	s_cselect_b32 s28, s12, s2
	s_add_i32 s57, 0, 0x14000
	ds_read_b128 v[134:137], v0
	ds_read_b128 v[138:141], v0 offset:1024
	ds_read_b128 v[142:145], v0 offset:2048
	ds_read_b128 v[146:149], v0 offset:3072
	v_add_u32_e32 v0, s57, v241
	ds_read_b128 v[150:153], v0
	ds_read_b128 v[154:157], v0 offset:1024
	ds_read_b128 v[158:161], v0 offset:2048
	ds_read_b128 v[162:165], v0 offset:3072
	s_mov_b32 s93, s31
	s_lshl_b64 s[26:27], s[30:31], 8
	v_add_u32_e32 v0, 0, v240
	v_lshl_add_u64 v[214:215], vcc, 0, v[130:131]
	s_add_i32 m0, s34, 0xc000
	ds_read_b128 v[166:169], v0
	ds_read_b128 v[170:173], v0 offset:1024
	ds_read_b128 v[174:177], v0 offset:2048
	ds_read_b128 v[178:181], v0 offset:3072
	ds_read_b128 v[182:185], v0 offset:4096
	ds_read_b128 v[186:189], v0 offset:5120
	ds_read_b128 v[190:193], v0 offset:6144
	ds_read_b128 v[210:213], v0 offset:7168
	global_load_lds_dwordx4 v[214:215], off
	v_lshl_add_u64 v[214:215], vcc, 0, v[132:133]
	s_add_i32 m0, s34, 0xe000
	s_nop 0
	global_load_lds_dwordx4 v[214:215], off
	s_waitcnt vmcnt(8)
	s_waitcnt lgkmcnt(0)
	s_barrier
	s_setprio 1
	s_waitcnt lgkmcnt(0)
	v_mfma_f32_16x16x32_bf16 v[126:129], v[134:137], v[166:169], v[126:129]
	v_mfma_f32_16x16x32_bf16 v[122:125], v[142:145], v[166:169], v[122:125]
	v_mfma_f32_16x16x32_bf16 v[110:113], v[134:137], v[174:177], v[110:113]
	v_mfma_f32_16x16x32_bf16 v[106:109], v[142:145], v[174:177], v[106:109]
	v_mfma_f32_16x16x32_bf16 v[98:101], v[134:137], v[182:185], v[98:101]
	v_mfma_f32_16x16x32_bf16 v[90:93], v[142:145], v[182:185], v[90:93]
	v_mfma_f32_16x16x32_bf16 v[82:85], v[134:137], v[190:193], v[82:85]
	v_mfma_f32_16x16x32_bf16 v[74:77], v[142:145], v[190:193], v[74:77]
	v_mfma_f32_16x16x32_bf16 v[126:129], v[138:141], v[170:173], v[126:129]
	v_mfma_f32_16x16x32_bf16 v[122:125], v[146:149], v[170:173], v[122:125]
	v_mfma_f32_16x16x32_bf16 v[110:113], v[138:141], v[178:181], v[110:113]
	v_mfma_f32_16x16x32_bf16 v[106:109], v[146:149], v[178:181], v[106:109]
	v_mfma_f32_16x16x32_bf16 v[98:101], v[138:141], v[186:189], v[98:101]
	v_mfma_f32_16x16x32_bf16 v[90:93], v[146:149], v[186:189], v[90:93]
	v_mfma_f32_16x16x32_bf16 v[82:85], v[138:141], v[210:213], v[82:85]
	v_mfma_f32_16x16x32_bf16 v[74:77], v[146:149], v[210:213], v[74:77]
	s_setprio 0
	s_setprio 1
	v_mfma_f32_16x16x32_bf16 v[118:121], v[150:153], v[166:169], v[118:121]
	v_mfma_f32_16x16x32_bf16 v[114:117], v[158:161], v[166:169], v[114:117]
	v_mfma_f32_16x16x32_bf16 v[102:105], v[150:153], v[174:177], v[102:105]
	v_mfma_f32_16x16x32_bf16 v[94:97], v[158:161], v[174:177], v[94:97]
	v_mfma_f32_16x16x32_bf16 v[86:89], v[150:153], v[182:185], v[86:89]
	v_mfma_f32_16x16x32_bf16 v[78:81], v[158:161], v[182:185], v[78:81]
	v_mfma_f32_16x16x32_bf16 v[70:73], v[150:153], v[190:193], v[70:73]
	v_mfma_f32_16x16x32_bf16 v[66:69], v[158:161], v[190:193], v[66:69]
	v_mfma_f32_16x16x32_bf16 v[118:121], v[154:157], v[170:173], v[118:121]
	v_mfma_f32_16x16x32_bf16 v[114:117], v[162:165], v[170:173], v[114:117]
	v_mfma_f32_16x16x32_bf16 v[102:105], v[154:157], v[178:181], v[102:105]
	v_mfma_f32_16x16x32_bf16 v[94:97], v[162:165], v[178:181], v[94:97]
	v_mfma_f32_16x16x32_bf16 v[86:89], v[154:157], v[186:189], v[86:89]
	v_mfma_f32_16x16x32_bf16 v[78:81], v[162:165], v[186:189], v[78:81]
	v_mfma_f32_16x16x32_bf16 v[70:73], v[154:157], v[210:213], v[70:73]
	v_mfma_f32_16x16x32_bf16 v[66:69], v[162:165], v[210:213], v[66:69]
	s_setprio 0
	s_barrier
	s_add_i32 s37, s37, s25
	v_mad_u64_u32 v[214:215], s[80:81], s92, v237, v[194:195]
	s_mov_b32 m0, s37
	ds_read_b128 v[166:169], v0 offset:16384
	ds_read_b128 v[170:173], v0 offset:17408
	ds_read_b128 v[174:177], v0 offset:18432
	ds_read_b128 v[178:181], v0 offset:19456
	ds_read_b128 v[182:185], v0 offset:20480
	ds_read_b128 v[186:189], v0 offset:21504
	ds_read_b128 v[190:193], v0 offset:22528
	ds_read_b128 v[210:213], v0 offset:23552
	s_lshl_b64 s[74:75], s[92:93], 8
	global_load_lds_dwordx4 v214, s[28:29]
	s_add_i32 m0, s37, 0x2000
	s_add_u32 s74, s28, s74
	v_mad_u64_u32 v[216:217], s[80:81], s92, v238, v[196:197]
	s_addc_u32 s75, s29, s75
	s_add_i32 s37, s57, s25
	global_load_lds_dwordx4 v216, s[28:29]
	s_mov_b32 m0, s37
	v_mad_u64_u32 v[218:219], s[80:81], s30, v235, v[194:195]
	global_load_lds_dwordx4 v214, s[74:75]
	s_add_i32 m0, s37, 0x2000
	v_mad_u64_u32 v[220:221], s[80:81], s30, v236, v[196:197]
	global_load_lds_dwordx4 v216, s[74:75]
	s_mov_b32 m0, s34
	v_mov_b32_e32 v215, v1
	global_load_lds_dwordx4 v218, s[8:9]
	s_mov_b32 m0, s35
	v_mov_b32_e32 v217, v1
	global_load_lds_dwordx4 v220, s[8:9]
	v_mov_b32_e32 v219, v1
	v_mov_b32_e32 v221, v1
	v_lshl_add_u64 v[222:223], s[28:29], 0, v[214:215]
	v_lshl_add_u64 v[224:225], s[28:29], 0, v[216:217]
	v_lshl_add_u64 v[214:215], s[74:75], 0, v[214:215]
	v_lshl_add_u64 v[216:217], s[74:75], 0, v[216:217]
	v_lshl_add_u64 v[226:227], s[8:9], 0, v[218:219]
	v_lshl_add_u64 v[228:229], s[8:9], 0, v[220:221]
	s_waitcnt vmcnt(8)
	s_waitcnt lgkmcnt(0)
	s_barrier
; #define PG8_LDA(dst, b, h) do { _Pragma("unroll") for (int m = 0; m < 4; ++m) _Pragma("unroll") for (int k = 0; k < 2; ++k) dst[m][k] = *(const LAS bf16x8*)(lds + PG8_SA(b, h) + aoff + m * 2048 + k * 1024); } while (0)
; #define PG8_LDB(dst, b, h) do { _Pragma("unroll") for (int n = 0; n < 2; ++n) _Pragma("unroll") for (int k = 0; k < 2; ++k) dst[n][k] = *(const LAS bf16x8*)(lds + PG8_SB(b, h) + boff + n * 2048 + k * 1024); } while (0)
; #define PG8_MMA(ai, bj, At, Bt) do { __builtin_amdgcn_s_setprio(1); _Pragma("unroll") for (int m = 0; m < 4; ++m) _Pragma("unroll") for (int n = 0; n < 2; ++n) _Pragma("unroll") for (int k = 0; k < 2; ++k) \
;         acc[ai][bj][m][n] = __builtin_amdgcn_mfma_f32_16x16x32_bf16(Bt[n][k], At[m][k], acc[ai][bj][m][n], 0, 0, 0); __builtin_amdgcn_s_setprio(0); } while (0)
; #define PG8_WAIT_V(n) asm volatile("s_waitcnt vmcnt(" #n ")" ::: "memory")
; #define PG8_WAIT_L(n) asm volatile("s_waitcnt lgkmcnt(" #n ")" ::: "memory")
; #define PG8_BAR __builtin_amdgcn_s_barrier()
; #define PG8_SCHED __builtin_amdgcn_sched_barrier(0)
; #define PG8_STA(bufoff, gbase, ld) PG8_STAGE(bufoff, gbase, RA0 * (unsigned)(ld) + CC0, RA1 * (unsigned)(ld) + CC1)
; __device__ __forceinline__ void gemm_phase(LAS unsigned char* lds, const Sched& S, const Epi& E) {
;     ...
;             PG8_WAIT_V(8); PG8_WAIT_L(0); PG8_BAR; PG8_MMA(1, 0, At, B0); PG8_MMA(1, 1, At, B1); PG8_BAR; PG8_SCHED;
;             PG8_LDB(B0, 1, 0); PG8_LDB(B1, 1, 1); PG8_SCHED; PG8_LDA(At, 1, 0); PG8_STA(PG8_SA(0, 1), a2 + xhA, xlda);
;             PG8_WAIT_V(8); PG8_WAIT_L(0); PG8_BAR; PG8_MMA(0, 0, At, B0); PG8_MMA(0, 1, At, B1); PG8_BAR; PG8_SCHED;
	s_setprio 1
	s_waitcnt lgkmcnt(0)
	v_mfma_f32_16x16x32_bf16 v[62:65], v[134:137], v[166:169], v[62:65]
	v_mfma_f32_16x16x32_bf16 v[58:61], v[142:145], v[166:169], v[58:61]
	v_mfma_f32_16x16x32_bf16 v[46:49], v[134:137], v[174:177], v[46:49]
	v_mfma_f32_16x16x32_bf16 v[42:45], v[142:145], v[174:177], v[42:45]
	v_mfma_f32_16x16x32_bf16 v[30:33], v[134:137], v[182:185], v[30:33]
	v_mfma_f32_16x16x32_bf16 v[26:29], v[142:145], v[182:185], v[26:29]
	v_mfma_f32_16x16x32_bf16 v[14:17], v[134:137], v[190:193], v[14:17]
	v_mfma_f32_16x16x32_bf16 v[10:13], v[142:145], v[190:193], v[10:13]
	v_mfma_f32_16x16x32_bf16 v[62:65], v[138:141], v[170:173], v[62:65]
	v_mfma_f32_16x16x32_bf16 v[58:61], v[146:149], v[170:173], v[58:61]
	v_mfma_f32_16x16x32_bf16 v[46:49], v[138:141], v[178:181], v[46:49]
	v_mfma_f32_16x16x32_bf16 v[42:45], v[146:149], v[178:181], v[42:45]
	v_mfma_f32_16x16x32_bf16 v[30:33], v[138:141], v[186:189], v[30:33]
	v_mfma_f32_16x16x32_bf16 v[26:29], v[146:149], v[186:189], v[26:29]
	v_mfma_f32_16x16x32_bf16 v[14:17], v[138:141], v[210:213], v[14:17]
	v_mfma_f32_16x16x32_bf16 v[10:13], v[146:149], v[210:213], v[10:13]
	s_setprio 0
	s_setprio 1
	v_mfma_f32_16x16x32_bf16 v[54:57], v[150:153], v[166:169], v[54:57]
	v_mfma_f32_16x16x32_bf16 v[50:53], v[158:161], v[166:169], v[50:53]
	v_mfma_f32_16x16x32_bf16 v[38:41], v[150:153], v[174:177], v[38:41]
	v_mfma_f32_16x16x32_bf16 v[34:37], v[158:161], v[174:177], v[34:37]
	v_mfma_f32_16x16x32_bf16 v[22:25], v[150:153], v[182:185], v[22:25]
	v_mfma_f32_16x16x32_bf16 v[18:21], v[158:161], v[182:185], v[18:21]
	v_mfma_f32_16x16x32_bf16 v[6:9], v[150:153], v[190:193], v[6:9]
	v_mfma_f32_16x16x32_bf16 v[2:5], v[158:161], v[190:193], v[2:5]
	v_mfma_f32_16x16x32_bf16 v[54:57], v[154:157], v[170:173], v[54:57]
	v_mfma_f32_16x16x32_bf16 v[50:53], v[162:165], v[170:173], v[50:53]
	v_mfma_f32_16x16x32_bf16 v[38:41], v[154:157], v[178:181], v[38:41]
	v_mfma_f32_16x16x32_bf16 v[34:37], v[162:165], v[178:181], v[34:37]
	v_mfma_f32_16x16x32_bf16 v[22:25], v[154:157], v[186:189], v[22:25]
	v_mfma_f32_16x16x32_bf16 v[18:21], v[162:165], v[186:189], v[18:21]
	v_mfma_f32_16x16x32_bf16 v[6:9], v[154:157], v[210:213], v[6:9]
	v_mfma_f32_16x16x32_bf16 v[2:5], v[162:165], v[210:213], v[2:5]
	s_setprio 0
	s_barrier
	s_add_i32 s28, 0, 0x18000
	s_add_i32 s29, 0, 0x1c000
	v_add_u32_e32 v146, s28, v241
	v_add_u32_e32 v162, s29, v241
	ds_read_b128 v[134:137], v146
	ds_read_b128 v[138:141], v146 offset:1024
	ds_read_b128 v[142:145], v146 offset:2048
	ds_read_b128 v[146:149], v146 offset:3072
	ds_read_b128 v[150:153], v162
	ds_read_b128 v[154:157], v162 offset:1024
	ds_read_b128 v[158:161], v162 offset:2048
	ds_read_b128 v[162:165], v162 offset:3072
	s_add_u32 s8, s8, s26
	s_addc_u32 s9, s9, s27
	s_mov_b32 m0, s39
	ds_read_b128 v[166:169], v0 offset:32768
	ds_read_b128 v[170:173], v0 offset:33792
	ds_read_b128 v[174:177], v0 offset:34816
	ds_read_b128 v[178:181], v0 offset:35840
	ds_read_b128 v[182:185], v0 offset:36864
	ds_read_b128 v[186:189], v0 offset:37888
	ds_read_b128 v[190:193], v0 offset:38912
	ds_read_b128 v[210:213], v0 offset:39936
	global_load_lds_dwordx4 v218, s[8:9]
	s_mov_b32 m0, s91
	s_nop 0
	global_load_lds_dwordx4 v220, s[8:9]
	s_waitcnt vmcnt(8)
	s_waitcnt lgkmcnt(0)
	s_barrier
	s_setprio 1
	s_waitcnt lgkmcnt(0)
	v_mfma_f32_16x16x32_bf16 v[126:129], v[134:137], v[166:169], v[126:129]
	v_mfma_f32_16x16x32_bf16 v[122:125], v[142:145], v[166:169], v[122:125]
	v_mfma_f32_16x16x32_bf16 v[110:113], v[134:137], v[174:177], v[110:113]
	v_mfma_f32_16x16x32_bf16 v[106:109], v[142:145], v[174:177], v[106:109]
	v_mfma_f32_16x16x32_bf16 v[98:101], v[134:137], v[182:185], v[98:101]
	v_mfma_f32_16x16x32_bf16 v[90:93], v[142:145], v[182:185], v[90:93]
	v_mfma_f32_16x16x32_bf16 v[82:85], v[134:137], v[190:193], v[82:85]
	v_mfma_f32_16x16x32_bf16 v[74:77], v[142:145], v[190:193], v[74:77]
	v_mfma_f32_16x16x32_bf16 v[126:129], v[138:141], v[170:173], v[126:129]
	v_mfma_f32_16x16x32_bf16 v[122:125], v[146:149], v[170:173], v[122:125]
	v_mfma_f32_16x16x32_bf16 v[110:113], v[138:141], v[178:181], v[110:113]
	v_mfma_f32_16x16x32_bf16 v[106:109], v[146:149], v[178:181], v[106:109]
	v_mfma_f32_16x16x32_bf16 v[98:101], v[138:141], v[186:189], v[98:101]
	v_mfma_f32_16x16x32_bf16 v[90:93], v[146:149], v[186:189], v[90:93]
	v_mfma_f32_16x16x32_bf16 v[82:85], v[138:141], v[210:213], v[82:85]
	v_mfma_f32_16x16x32_bf16 v[74:77], v[146:149], v[210:213], v[74:77]
	s_setprio 0
	s_setprio 1
	v_mfma_f32_16x16x32_bf16 v[118:121], v[150:153], v[166:169], v[118:121]
	v_mfma_f32_16x16x32_bf16 v[114:117], v[158:161], v[166:169], v[114:117]
	v_mfma_f32_16x16x32_bf16 v[102:105], v[150:153], v[174:177], v[102:105]
	v_mfma_f32_16x16x32_bf16 v[94:97], v[158:161], v[174:177], v[94:97]
	v_mfma_f32_16x16x32_bf16 v[86:89], v[150:153], v[182:185], v[86:89]
	v_mfma_f32_16x16x32_bf16 v[78:81], v[158:161], v[182:185], v[78:81]
	v_mfma_f32_16x16x32_bf16 v[70:73], v[150:153], v[190:193], v[70:73]
	v_mfma_f32_16x16x32_bf16 v[66:69], v[158:161], v[190:193], v[66:69]
	v_mfma_f32_16x16x32_bf16 v[118:121], v[154:157], v[170:173], v[118:121]
	v_mfma_f32_16x16x32_bf16 v[114:117], v[162:165], v[170:173], v[114:117]
	v_mfma_f32_16x16x32_bf16 v[102:105], v[154:157], v[178:181], v[102:105]
	v_mfma_f32_16x16x32_bf16 v[94:97], v[162:165], v[178:181], v[94:97]
	v_mfma_f32_16x16x32_bf16 v[86:89], v[154:157], v[186:189], v[86:89]
	v_mfma_f32_16x16x32_bf16 v[78:81], v[162:165], v[186:189], v[78:81]
	v_mfma_f32_16x16x32_bf16 v[70:73], v[154:157], v[210:213], v[70:73]
	v_mfma_f32_16x16x32_bf16 v[66:69], v[162:165], v[210:213], v[66:69]
	s_setprio 0
	s_barrier
; #define PG8_LDA(dst, b, h) do { _Pragma("unroll") for (int m = 0; m < 4; ++m) _Pragma("unroll") for (int k = 0; k < 2; ++k) dst[m][k] = *(const LAS bf16x8*)(lds + PG8_SA(b, h) + aoff + m * 2048 + k * 1024); } while (0)
; #define PG8_MMA(ai, bj, At, Bt) do { __builtin_amdgcn_s_setprio(1); _Pragma("unroll") for (int m = 0; m < 4; ++m) _Pragma("unroll") for (int n = 0; n < 2; ++n) _Pragma("unroll") for (int k = 0; k < 2; ++k) \
;         acc[ai][bj][m][n] = __builtin_amdgcn_mfma_f32_16x16x32_bf16(Bt[n][k], At[m][k], acc[ai][bj][m][n], 0, 0, 0); __builtin_amdgcn_s_setprio(0); } while (0)
; #define PG8_WAIT_V(n) asm volatile("s_waitcnt vmcnt(" #n ")" ::: "memory")
; #define PG8_WAIT_L(n) asm volatile("s_waitcnt lgkmcnt(" #n ")" ::: "memory")
; #define PG8_BAR __builtin_amdgcn_s_barrier()
; #define PG8_SCHED __builtin_amdgcn_sched_barrier(0)
; #define PG8_STA(bufoff, gbase, ld) PG8_STAGE(bufoff, gbase, RA0 * (unsigned)(ld) + CC0, RA1 * (unsigned)(ld) + CC1)
; #define PG8_STB(bufoff, gbase, ld) PG8_STAGE(bufoff, gbase, RB0 * (unsigned)(ld) + CC0, RB1 * (unsigned)(ld) + CC1)
; __device__ __forceinline__ void gemm_phase(LAS unsigned char* lds, const Sched& S, const Epi& E) {
;     ...
;             PG8_LDA(At, 1, 1); PG8_STB(PG8_SB(1, 0), b3, xldb); PG8_STB(PG8_SB(1, 1), b3 + xhB, xldb); PG8_STA(PG8_SA(1, 0), a3, xlda);
;             PG8_WAIT_V(8); PG8_WAIT_L(0); PG8_BAR; PG8_MMA(1, 0, At, B0); PG8_MMA(1, 1, At, B1); PG8_BAR; PG8_SCHED;
;         }
;         if (!has_next) {
	s_add_i32 s8, s28, s25
	v_lshl_add_u64 v[218:219], v[222:223], 0, s[52:53]
	s_mov_b32 m0, s8
	ds_read_b128 v[166:169], v0 offset:49152
	ds_read_b128 v[170:173], v0 offset:50176
	ds_read_b128 v[174:177], v0 offset:51200
	ds_read_b128 v[178:181], v0 offset:52224
	ds_read_b128 v[182:185], v0 offset:53248
	ds_read_b128 v[186:189], v0 offset:54272
	ds_read_b128 v[190:193], v0 offset:55296
	ds_read_b128 v[210:213], v0 offset:56320
	global_load_lds_dwordx4 v[218:219], off
	v_lshl_add_u64 v[218:219], v[224:225], 0, s[52:53]
	s_add_i32 m0, s8, 0x2000
	s_add_i32 s8, s29, s25
	global_load_lds_dwordx4 v[218:219], off
	v_lshl_add_u64 v[214:215], v[214:215], 0, s[52:53]
	s_mov_b32 m0, s8
	s_nop 0
	global_load_lds_dwordx4 v[214:215], off
	v_lshl_add_u64 v[214:215], v[216:217], 0, s[52:53]
	s_add_i32 m0, s8, 0x2000
	s_nop 0
	global_load_lds_dwordx4 v[214:215], off
	v_lshl_add_u64 v[214:215], v[226:227], 0, s[52:53]
	s_mov_b32 m0, s90
	s_nop 0
	global_load_lds_dwordx4 v[214:215], off
	v_lshl_add_u64 v[214:215], v[228:229], 0, s[52:53]
	s_mov_b32 m0, s73
	s_nop 0
	global_load_lds_dwordx4 v[214:215], off
	s_waitcnt vmcnt(8)
	s_waitcnt lgkmcnt(0)
	s_barrier
	s_setprio 1
	s_waitcnt lgkmcnt(0)
	v_mfma_f32_16x16x32_bf16 v[62:65], v[134:137], v[166:169], v[62:65]
	v_mfma_f32_16x16x32_bf16 v[58:61], v[142:145], v[166:169], v[58:61]
	v_mfma_f32_16x16x32_bf16 v[46:49], v[134:137], v[174:177], v[46:49]
	v_mfma_f32_16x16x32_bf16 v[42:45], v[142:145], v[174:177], v[42:45]
	v_mfma_f32_16x16x32_bf16 v[30:33], v[134:137], v[182:185], v[30:33]
	v_mfma_f32_16x16x32_bf16 v[26:29], v[142:145], v[182:185], v[26:29]
	v_mfma_f32_16x16x32_bf16 v[14:17], v[134:137], v[190:193], v[14:17]
	v_mfma_f32_16x16x32_bf16 v[10:13], v[142:145], v[190:193], v[10:13]
	v_mfma_f32_16x16x32_bf16 v[62:65], v[138:141], v[170:173], v[62:65]
	v_mfma_f32_16x16x32_bf16 v[58:61], v[146:149], v[170:173], v[58:61]
	v_mfma_f32_16x16x32_bf16 v[46:49], v[138:141], v[178:181], v[46:49]
	v_mfma_f32_16x16x32_bf16 v[42:45], v[146:149], v[178:181], v[42:45]
	v_mfma_f32_16x16x32_bf16 v[30:33], v[138:141], v[186:189], v[30:33]
	v_mfma_f32_16x16x32_bf16 v[26:29], v[146:149], v[186:189], v[26:29]
	v_mfma_f32_16x16x32_bf16 v[14:17], v[138:141], v[210:213], v[14:17]
	v_mfma_f32_16x16x32_bf16 v[10:13], v[146:149], v[210:213], v[10:13]
	s_setprio 0
	s_setprio 1
	v_mfma_f32_16x16x32_bf16 v[54:57], v[150:153], v[166:169], v[54:57]
	v_mfma_f32_16x16x32_bf16 v[50:53], v[158:161], v[166:169], v[50:53]
	v_mfma_f32_16x16x32_bf16 v[38:41], v[150:153], v[174:177], v[38:41]
	v_mfma_f32_16x16x32_bf16 v[34:37], v[158:161], v[174:177], v[34:37]
	v_mfma_f32_16x16x32_bf16 v[22:25], v[150:153], v[182:185], v[22:25]
	v_mfma_f32_16x16x32_bf16 v[18:21], v[158:161], v[182:185], v[18:21]
	v_mfma_f32_16x16x32_bf16 v[6:9], v[150:153], v[190:193], v[6:9]
	v_mfma_f32_16x16x32_bf16 v[2:5], v[158:161], v[190:193], v[2:5]
	v_mfma_f32_16x16x32_bf16 v[54:57], v[154:157], v[170:173], v[54:57]
	v_mfma_f32_16x16x32_bf16 v[50:53], v[162:165], v[170:173], v[50:53]
	v_mfma_f32_16x16x32_bf16 v[38:41], v[154:157], v[178:181], v[38:41]
	v_mfma_f32_16x16x32_bf16 v[34:37], v[162:165], v[178:181], v[34:37]
	v_mfma_f32_16x16x32_bf16 v[22:25], v[154:157], v[186:189], v[22:25]
	v_mfma_f32_16x16x32_bf16 v[18:21], v[162:165], v[186:189], v[18:21]
	v_mfma_f32_16x16x32_bf16 v[6:9], v[154:157], v[210:213], v[6:9]
	v_mfma_f32_16x16x32_bf16 v[2:5], v[162:165], v[210:213], v[2:5]
	s_setprio 0
	s_barrier
	s_add_u32 vcc_lo, vcc_lo, 0x100
	s_addc_u32 vcc_hi, vcc_hi, 0
	s_add_u32 s2, s2, 0x100
	s_addc_u32 s72, s72, 0
	s_cmp_ge_i32 s24, s68
	s_mov_b32 s8, s24
	s_cbranch_scc0 .LBB0_263
	s_mov_b32 s92, s3
	s_movk_i32 s93, 0x3fff
	s_movk_i32 s3, 0x2000
	s_and_b64 vcc, exec, s[44:45]
	s_cbranch_vccz .LBB0_266
